# v66 + write-through conversion stores + barrier leader's workspace-pointer load hoisted
# baseline (speedup 1.0000x reference)
; #define LAS __attribute__((address_space(3)))
; DI unsigned pk2(float a, float b) { f32x2 f = {a, b}; bf16v2 r = __builtin_convertvector(f, bf16v2); return __builtin_bit_cast(unsigned, r); }
; DI void conv_item(int lane, LAS unsigned char* wl, const float* src, const float* src2, const float* gain, bf16_t* dst, int ld, int K, int mode, int coff, int item) {
;     ...
;     for (int kb = 0; kb < 256; kb += 64) {
;         float v[64];
; #pragma unroll
;         for (int j = 0; j < 64; ++j) v[j] = zero ? 0.f : __builtin_nontemporal_load(sp + (size_t)(kb + j) * ld);
;         if (gain) {
; #pragma unroll
;             for (int j = 0; j < 64; ++j) v[j] *= gain[k0 + kb + j];
;         }
; #pragma unroll
;         for (int q = 0; q < 8; ++q) { u32x4 w; w.x = pk2(v[8 * q], v[8 * q + 1]); w.y = pk2(v[8 * q + 2], v[8 * q + 3]); w.z = pk2(v[8 * q + 4], v[8 * q + 5]); w.w = pk2(v[8 * q + 6], v[8 * q + 7]);
;             *(LAS u32x4*)(wl + lane * 144 + q * 16) = w; }
;         asm volatile("" ::: "memory");
; #pragma unroll
;         for (int j = 0; j < 8; ++j) { const u32x4 w = *(const LAS u32x4*)(wl + (8 * j + (lane >> 3)) * 144 + (lane & 7) * 16); *(u32x4*)(dp + (j & 3) * rstep + (j >> 2) * hstep + kb) = w; }
;         asm volatile("" ::: "memory");
;     }
.LBB0_91:
	s_waitcnt vmcnt(0)
	v_cvt_pk_bf16_f32 v156, v156, v157
	v_cvt_pk_bf16_f32 v157, v158, v159
	v_cvt_pk_bf16_f32 v158, v160, v161
	v_cvt_pk_bf16_f32 v159, v162, v163
	ds_write_b128 v230, v[156:159]
	v_cvt_pk_bf16_f32 v156, v164, v165
	v_cvt_pk_bf16_f32 v157, v166, v167
	v_cvt_pk_bf16_f32 v158, v168, v169
	v_cvt_pk_bf16_f32 v159, v170, v171
	ds_write_b128 v230, v[156:159] offset:16
	v_cvt_pk_bf16_f32 v156, v172, v173
	v_cvt_pk_bf16_f32 v157, v174, v175
	v_cvt_pk_bf16_f32 v158, v176, v177
	v_cvt_pk_bf16_f32 v159, v178, v179
	ds_write_b128 v230, v[156:159] offset:32
	v_cvt_pk_bf16_f32 v156, v180, v181
	v_cvt_pk_bf16_f32 v157, v182, v183
	v_cvt_pk_bf16_f32 v158, v184, v185
	v_cvt_pk_bf16_f32 v159, v186, v187
	ds_write_b128 v230, v[156:159] offset:48
	v_cvt_pk_bf16_f32 v156, v188, v189
	v_cvt_pk_bf16_f32 v157, v190, v191
	v_cvt_pk_bf16_f32 v158, v192, v193
	v_cvt_pk_bf16_f32 v159, v194, v195
	ds_write_b128 v230, v[156:159] offset:64
	v_cvt_pk_bf16_f32 v156, v196, v197
	v_cvt_pk_bf16_f32 v157, v198, v199
	v_cvt_pk_bf16_f32 v158, v200, v201
	v_cvt_pk_bf16_f32 v159, v202, v203
	ds_write_b128 v230, v[156:159] offset:80
	v_cvt_pk_bf16_f32 v156, v204, v205
	v_cvt_pk_bf16_f32 v157, v206, v207
	v_cvt_pk_bf16_f32 v158, v208, v209
	v_cvt_pk_bf16_f32 v159, v210, v211
	ds_write_b128 v230, v[156:159] offset:96
	v_cvt_pk_bf16_f32 v156, v212, v213
	v_cvt_pk_bf16_f32 v157, v214, v215
	v_cvt_pk_bf16_f32 v158, v216, v217
	v_cvt_pk_bf16_f32 v159, v218, v219
	ds_write_b128 v230, v[156:159] offset:112
	ds_read_b128 v[156:159], v231
	ds_read_b128 v[160:163], v231 offset:1152
	v_lshl_add_u64 v[164:165], v[152:153], 0, s[74:75]
	v_lshl_add_u64 v[168:169], v[142:143], 0, s[74:75]
	s_add_i32 s80, s80, 64
	s_waitcnt lgkmcnt(1)
	global_store_dwordx4 v[164:165], v[156:159], off sc1
	ds_read_b128 v[156:159], v231 offset:2304
	v_lshl_add_u64 v[164:165], v[150:151], 0, s[74:75]
	s_waitcnt lgkmcnt(1)
	global_store_dwordx4 v[164:165], v[160:163], off sc1
	ds_read_b128 v[160:163], v231 offset:3456
	v_lshl_add_u64 v[164:165], v[148:149], 0, s[74:75]
	s_waitcnt lgkmcnt(1)
	global_store_dwordx4 v[164:165], v[156:159], off sc1
	ds_read_b128 v[156:159], v231 offset:4608
	v_lshl_add_u64 v[164:165], v[146:147], 0, s[74:75]
	s_waitcnt lgkmcnt(1)
	global_store_dwordx4 v[164:165], v[160:163], off sc1
	v_lshl_add_u64 v[164:165], v[144:145], 0, s[74:75]
	ds_read_b128 v[160:163], v231 offset:5760
	s_waitcnt lgkmcnt(1)
	global_store_dwordx4 v[164:165], v[156:159], off sc1
	ds_read_b128 v[156:159], v231 offset:6912
	ds_read_b128 v[164:167], v231 offset:8064
	s_add_u32 s76, s76, 0x100
	s_waitcnt lgkmcnt(2)
	global_store_dwordx4 v[168:169], v[160:163], off sc1
	s_addc_u32 s77, s77, 0
	v_lshl_add_u64 v[12:13], v[12:13], 0, s[40:41]
	v_lshl_add_u64 v[160:161], v[140:141], 0, s[74:75]
	s_waitcnt lgkmcnt(1)
	global_store_dwordx4 v[160:161], v[156:159], off sc1
	v_lshl_add_u64 v[14:15], v[14:15], 0, s[40:41]
	v_lshl_add_u64 v[16:17], v[16:17], 0, s[40:41]
	v_lshl_add_u64 v[156:157], v[138:139], 0, s[74:75]
	s_waitcnt lgkmcnt(0)
	global_store_dwordx4 v[156:157], v[164:167], off sc1
	v_lshl_add_u64 v[18:19], v[18:19], 0, s[40:41]
	v_lshl_add_u64 v[20:21], v[20:21], 0, s[40:41]
	v_lshl_add_u64 v[22:23], v[22:23], 0, s[40:41]
	v_lshl_add_u64 v[24:25], v[24:25], 0, s[40:41]
	v_lshl_add_u64 v[26:27], v[26:27], 0, s[40:41]
	v_lshl_add_u64 v[28:29], v[28:29], 0, s[40:41]
	v_lshl_add_u64 v[30:31], v[30:31], 0, s[40:41]
	v_lshl_add_u64 v[32:33], v[32:33], 0, s[40:41]
	v_lshl_add_u64 v[34:35], v[34:35], 0, s[40:41]
	v_lshl_add_u64 v[36:37], v[36:37], 0, s[40:41]
	v_lshl_add_u64 v[38:39], v[38:39], 0, s[40:41]
	v_lshl_add_u64 v[40:41], v[40:41], 0, s[40:41]
	v_lshl_add_u64 v[42:43], v[42:43], 0, s[40:41]
	v_lshl_add_u64 v[44:45], v[44:45], 0, s[40:41]
	v_lshl_add_u64 v[46:47], v[46:47], 0, s[40:41]
	v_lshl_add_u64 v[48:49], v[48:49], 0, s[40:41]
	v_lshl_add_u64 v[50:51], v[50:51], 0, s[40:41]
	v_lshl_add_u64 v[52:53], v[52:53], 0, s[40:41]
	v_lshl_add_u64 v[54:55], v[54:55], 0, s[40:41]
	v_lshl_add_u64 v[56:57], v[56:57], 0, s[40:41]
	v_lshl_add_u64 v[58:59], v[58:59], 0, s[40:41]
	v_lshl_add_u64 v[60:61], v[60:61], 0, s[40:41]
	v_lshl_add_u64 v[62:63], v[62:63], 0, s[40:41]
	v_lshl_add_u64 v[64:65], v[64:65], 0, s[40:41]
	v_lshl_add_u64 v[66:67], v[66:67], 0, s[40:41]
	v_lshl_add_u64 v[68:69], v[68:69], 0, s[40:41]
	v_lshl_add_u64 v[70:71], v[70:71], 0, s[40:41]
	v_lshl_add_u64 v[72:73], v[72:73], 0, s[40:41]
	v_lshl_add_u64 v[74:75], v[74:75], 0, s[40:41]
	v_lshl_add_u64 v[76:77], v[76:77], 0, s[40:41]
	v_lshl_add_u64 v[78:79], v[78:79], 0, s[40:41]
	v_lshl_add_u64 v[80:81], v[80:81], 0, s[40:41]
	v_lshl_add_u64 v[82:83], v[82:83], 0, s[40:41]
	v_lshl_add_u64 v[84:85], v[84:85], 0, s[40:41]
	v_lshl_add_u64 v[86:87], v[86:87], 0, s[40:41]
	v_lshl_add_u64 v[88:89], v[88:89], 0, s[40:41]
	v_lshl_add_u64 v[90:91], v[90:91], 0, s[40:41]
	v_lshl_add_u64 v[92:93], v[92:93], 0, s[40:41]
	v_lshl_add_u64 v[94:95], v[94:95], 0, s[40:41]
	v_lshl_add_u64 v[96:97], v[96:97], 0, s[40:41]
	v_lshl_add_u64 v[98:99], v[98:99], 0, s[40:41]
	v_lshl_add_u64 v[100:101], v[100:101], 0, s[40:41]
	v_lshl_add_u64 v[102:103], v[102:103], 0, s[40:41]
	v_lshl_add_u64 v[104:105], v[104:105], 0, s[40:41]
	v_lshl_add_u64 v[106:107], v[106:107], 0, s[40:41]
	v_lshl_add_u64 v[108:109], v[108:109], 0, s[40:41]
	v_lshl_add_u64 v[110:111], v[110:111], 0, s[40:41]
	v_lshl_add_u64 v[112:113], v[112:113], 0, s[40:41]
	v_lshl_add_u64 v[114:115], v[114:115], 0, s[40:41]
	v_lshl_add_u64 v[116:117], v[116:117], 0, s[40:41]
	v_lshl_add_u64 v[118:119], v[118:119], 0, s[40:41]
	v_lshl_add_u64 v[120:121], v[120:121], 0, s[40:41]
	v_lshl_add_u64 v[122:123], v[122:123], 0, s[40:41]
	v_lshl_add_u64 v[124:125], v[124:125], 0, s[40:41]
	v_lshl_add_u64 v[126:127], v[126:127], 0, s[40:41]
	v_lshl_add_u64 v[128:129], v[128:129], 0, s[40:41]
	v_lshl_add_u64 v[130:131], v[130:131], 0, s[40:41]
	v_lshl_add_u64 v[132:133], v[132:133], 0, s[40:41]
	v_lshl_add_u64 v[134:135], v[134:135], 0, s[40:41]
	v_lshl_add_u64 v[136:137], v[136:137], 0, s[40:41]
	v_lshl_add_u64 v[138:139], v[138:139], 0, s[68:69]
	v_lshl_add_u64 v[140:141], v[140:141], 0, s[68:69]
	v_lshl_add_u64 v[142:143], v[142:143], 0, s[68:69]
	v_lshl_add_u64 v[144:145], v[144:145], 0, s[68:69]
	v_lshl_add_u64 v[146:147], v[146:147], 0, s[68:69]
	v_lshl_add_u64 v[148:149], v[148:149], 0, s[68:69]
	v_lshl_add_u64 v[150:151], v[150:151], 0, s[68:69]
	v_lshl_add_u64 v[152:153], v[152:153], 0, s[68:69]
	s_cmpk_gt_u32 s80, 0xbf
	v_lshl_add_u64 v[154:155], v[154:155], 0, s[40:41]
	s_cbranch_scc1 .LBB0_22

; #define LAS __attribute__((address_space(3)))
; #define GP CP& p = *kparams()
; #define SEAM(k) do { if (IN(k) && IN((k) + 1)) { GP; grid_bar((unsigned*)(p.ws + OFF_BAR), (volatile LAS unsigned*)(lds + LDS_MAIN), wid); if (PROBE_BAR) grid_bar((unsigned*)(p.ws + OFF_BAR), (volatile LAS unsigned*)(lds + LDS_MAIN), wid); } } while (0)
; DI void grid_bar(unsigned* bar, volatile LAS unsigned* st, int wid) {
;     asm volatile("s_waitcnt vmcnt(0)" ::: "memory");
;     __syncthreads();
;     if (wid == 0) {
; __global__ void __launch_bounds__(NTHR, 2) mega(Params pv) {
;     ...
;     if (IN(0)) { GP; if (PROBE_PH == 0) phase0(p, lds, wid); phase0(p, lds, wid); }
;     SEAM(0);
.LBB0_241:
	s_cmp_gt_i32 s35, 1
	s_cselect_b64 s[2:3], -1, 0
	s_and_b64 s[4:5], s[36:37], s[2:3]
	s_andn2_b64 vcc, exec, s[4:5]
	s_cbranch_vccnz .LBB0_297
	s_load_dwordx2 s[8:9], s[0:1], 0xa8
	s_waitcnt vmcnt(0)
	s_cmp_gt_u32 s88, 63
	s_barrier
	s_cbranch_scc1 .Lbi_0
	s_mov_b32 s99, 0
	s_branch .Lbs_entry

; #define LAS __attribute__((address_space(3)))
; DI void grid_bar(unsigned* bar, volatile LAS unsigned* st, int wid) {
;     asm volatile("s_waitcnt vmcnt(0)" ::: "memory");
;     __syncthreads();
;     if (wid == 0) {
.Lconv_skip_0:
	s_cmp_gt_i32 s35, 2
	s_cselect_b64 s[2:3], -1, 0
	s_and_b64 s[4:5], s[8:9], s[2:3]
	s_andn2_b64 vcc, exec, s[4:5]
	s_cbranch_vccnz .LBB0_454
	s_load_dwordx2 s[8:9], s[0:1], 0xa8
	s_waitcnt vmcnt(0)
	s_cmp_gt_u32 s88, 63
	s_waitcnt vmcnt(0) lgkmcnt(0)
	s_barrier
	s_cbranch_scc1 .Lbi_1
	s_mov_b32 s99, 1
	s_branch .Lbs_entry

; #define LAS __attribute__((address_space(3)))
; DI void grid_bar(unsigned* bar, volatile LAS unsigned* st, int wid) {
;     asm volatile("s_waitcnt vmcnt(0)" ::: "memory");
;     __syncthreads();
;     if (wid == 0) {
.LBB0_471:
	s_cmp_gt_i32 s35, 3
	s_cselect_b64 s[2:3], -1, 0
	s_and_b64 s[4:5], s[16:17], s[2:3]
	s_andn2_b64 vcc, exec, s[4:5]
	s_cbranch_vccnz .LBB0_527
	s_load_dwordx2 s[8:9], s[0:1], 0xa8
	s_waitcnt vmcnt(0)
	s_cmp_gt_u32 s88, 63
	s_waitcnt vmcnt(0) lgkmcnt(0)
	s_barrier
	s_cbranch_scc1 .Lbi_2
	s_mov_b32 s99, 2
	s_branch .Lbs_entry

; #define LAS __attribute__((address_space(3)))
; DI void grid_bar(unsigned* bar, volatile LAS unsigned* st, int wid) {
;     asm volatile("s_waitcnt vmcnt(0)" ::: "memory");
;     __syncthreads();
;     if (wid == 0) {
.Lp2_skip:
	s_cmp_gt_i32 s35, 4
	s_cselect_b64 s[2:3], -1, 0
	s_and_b64 s[4:5], s[4:5], s[2:3]
	s_andn2_b64 vcc, exec, s[4:5]
	s_cbranch_vccnz .LBB0_602
	s_load_dwordx2 s[8:9], s[0:1], 0xa8
	s_waitcnt vmcnt(0)
	s_cmp_gt_u32 s88, 63
	s_waitcnt vmcnt(0) lgkmcnt(0)
	s_barrier
	s_cbranch_scc1 .Lbi_3
	s_mov_b32 s99, 3
	s_branch .Lbs_entry

; #define LAS __attribute__((address_space(3)))
; DI void grid_bar(unsigned* bar, volatile LAS unsigned* st, int wid) {
;     asm volatile("s_waitcnt vmcnt(0)" ::: "memory");
;     __syncthreads();
;     if (wid == 0) {
.LBB0_641:
	s_cmp_gt_i32 s35, 5
	s_cselect_b64 s[2:3], -1, 0
	s_and_b64 s[4:5], s[8:9], s[2:3]
	s_andn2_b64 vcc, exec, s[4:5]
	s_cbranch_vccnz .LBB0_697
	s_load_dwordx2 s[8:9], s[0:1], 0xa8
	s_waitcnt vmcnt(0)
	s_cmp_gt_u32 s88, 63
	s_waitcnt vmcnt(0) lgkmcnt(0)
	s_barrier
	s_cbranch_scc1 .Lbi_4
	s_mov_b32 s99, 4
	s_branch .Lbs_entry

; #define LAS __attribute__((address_space(3)))
; DI void grid_bar(unsigned* bar, volatile LAS unsigned* st, int wid) {
;     asm volatile("s_waitcnt vmcnt(0)" ::: "memory");
;     __syncthreads();
;     if (wid == 0) {
.Lconv_tramp_skip:
	s_cmp_gt_i32 s35, 6
	s_cselect_b64 s[2:3], -1, 0
	s_and_b64 s[4:5], s[4:5], s[2:3]
	s_andn2_b64 vcc, exec, s[4:5]
	s_cbranch_vccnz .LBB0_766
	s_load_dwordx2 s[8:9], s[0:1], 0xa8
	s_waitcnt vmcnt(0)
	s_cmp_gt_u32 s88, 63
	s_waitcnt vmcnt(0) lgkmcnt(0)
	s_barrier
	s_cbranch_scc1 .Lbi_5
	s_mov_b32 s99, 5
	s_branch .Lbs_entry

; #define LAS __attribute__((address_space(3)))
; DI int lane_id() { int l = __builtin_amdgcn_mbcnt_hi(-1, __builtin_amdgcn_mbcnt_lo(-1, 0)); asm volatile("" : "+v"(l)); return l; }
; DI unsigned xb_ld(unsigned* q) { return __hip_atomic_load(q, __ATOMIC_RELAXED, __HIP_MEMORY_SCOPE_AGENT); }
; DI unsigned xb_xcc_id() { return (unsigned)__builtin_amdgcn_s_getreg((3 << 11) | 20) & 0xFu; }
; DI void xcd_barrier_complete(unsigned* bar, unsigned x, unsigned& nloc, unsigned& nx) {
;     const unsigned G = gridDim.x;
;     unsigned sum, cnt, mine, sp = 0u;
;     for (;;) {
;         sum = 0u; cnt = 0u; mine = 0u;
; #pragma unroll
;         for (unsigned j = 0; j < 16; ++j) { const unsigned c = xb_ld(&bar[XB_XCNT(j)]); sum += c; cnt += (c > 0u) ? 1u : 0u; mine = (j == x) ? c : mine; }
; DI void grid_bar(unsigned* bar, volatile LAS unsigned* st, int wid) {
;     asm volatile("s_waitcnt vmcnt(0)" ::: "memory");
;     __syncthreads();
;     if (wid == 0) {
;         if (lane_id() == 0) {
;             __builtin_amdgcn_s_waitcnt(0);
;             const unsigned x = xb_xcc_id();
;             unsigned nloc = st[0], nx = st[1];
;             if (nloc == 0u) { xcd_barrier_complete(bar, x, nloc, nx); st[0] = nloc; st[1] = nx; }
.LBB0_805:
	s_cmp_gt_i32 s35, 7
	s_cselect_b64 s[2:3], -1, 0
	s_and_b64 s[4:5], s[8:9], s[2:3]
	s_andn2_b64 vcc, exec, s[4:5]
	s_cbranch_vccnz .LBB0_861
	s_load_dwordx2 s[8:9], s[0:1], 0xa8
	s_waitcnt vmcnt(0)
	s_cmp_gt_u32 s88, 63
	s_waitcnt vmcnt(0) lgkmcnt(0)
	s_barrier
	s_cbranch_scc1 .Lbi_6
	s_mov_b32 s99, 6
.Lbs_entry:
	v_mbcnt_hi_u32_b32 v0, -1, v254
	s_nop 0
	v_cmp_eq_u32_e32 vcc, 0, v0
	s_and_saveexec_b64 s[96:97], vcc
	s_cbranch_execz .LBB0_859
	s_add_i32 s11, 0, 0x20000
	v_mov_b32_e32 v0, s11
	s_waitcnt vmcnt(0) expcnt(0) lgkmcnt(0)
	s_getreg_b32 s10, hwreg(HW_REG_XCC_ID, 0, 4)
	ds_read_b32 v2, v0
	s_add_i32 s11, 0, 0x20004
	v_mov_b32_e32 v0, s11
	ds_read_b32 v0, v0
	s_and_b32 s54, s10, 15
	s_waitcnt lgkmcnt(1)
	v_cmp_ne_u32_e32 vcc, 0, v2
	s_cbranch_vccnz .LBB0_823
	s_add_u32 s10, s8, 0xcd80200
	s_addc_u32 s11, s9, 0
	s_add_u32 s12, s8, 0xcd80400
	s_addc_u32 s13, s9, 0
	s_add_u32 s14, s8, 0xcd80500
	s_addc_u32 s15, s9, 0
	s_add_u32 s16, s8, 0xcd80600
	s_addc_u32 s17, s9, 0
	s_add_u32 s18, s8, 0xcd80700
	s_addc_u32 s19, s9, 0
	s_add_u32 s20, s8, 0xcd80800
	s_addc_u32 s21, s9, 0
	s_add_u32 s22, s8, 0xcd80900
	s_addc_u32 s23, s9, 0
	s_add_u32 s24, s8, 0xcd80a00
	s_addc_u32 s25, s9, 0
	s_add_u32 s26, s8, 0xcd80b00
	s_addc_u32 s27, s9, 0
	s_add_u32 s28, s8, 0xcd80c00
	s_addc_u32 s29, s9, 0
	s_add_u32 s30, s8, 0xcd80d00
	s_addc_u32 s31, s9, 0
	s_add_u32 s36, s8, 0xcd80e00
	s_addc_u32 s37, s9, 0
	s_add_u32 s38, s8, 0xcd80f00
	s_addc_u32 s39, s9, 0
	s_add_u32 s40, s8, 0xcd81000
	s_addc_u32 s41, s9, 0
	s_add_u32 s42, s8, 0xcd81100
	s_addc_u32 s43, s9, 0
	s_add_u32 s44, s8, 0xcd81200
	s_addc_u32 s45, s9, 0
	s_add_u32 s46, s8, 0xcd81300
	s_addc_u32 s47, s9, 0
	s_mov_b32 s55, 1
	v_mov_b32_e32 v16, 0
	s_branch .LBB0_811

; #define LAS __attribute__((address_space(3)))
; DI void grid_bar(unsigned* bar, volatile LAS unsigned* st, int wid) {
;     asm volatile("s_waitcnt vmcnt(0)" ::: "memory");
;     __syncthreads();
;     if (wid == 0) {
.Lconv_skip_2:
	s_cmp_gt_i32 s35, 8
	s_cselect_b64 s[2:3], -1, 0
	s_and_b64 s[4:5], s[8:9], s[2:3]
	s_andn2_b64 vcc, exec, s[4:5]
	s_cbranch_vccnz .LBB0_954
	s_load_dwordx2 s[8:9], s[0:1], 0xa8
	s_waitcnt vmcnt(0)
	s_cmp_gt_u32 s88, 63
	s_waitcnt vmcnt(0) lgkmcnt(0)
	s_barrier
	s_cbranch_scc1 .Lbi_7
	s_mov_b32 s99, 7
	s_branch .Lbs_entry

; #define LAS __attribute__((address_space(3)))
; DI void grid_bar(unsigned* bar, volatile LAS unsigned* st, int wid) {
;     asm volatile("s_waitcnt vmcnt(0)" ::: "memory");
;     __syncthreads();
;     if (wid == 0) {
.Lconv_skip_3:
	s_cmp_gt_i32 s35, 9
	s_cselect_b64 s[4:5], -1, 0
	s_and_b64 s[2:3], s[2:3], s[4:5]
	s_andn2_b64 vcc, exec, s[2:3]
	s_cbranch_vccnz .LBB0_1073
	s_load_dwordx2 s[8:9], s[0:1], 0xa8
	s_waitcnt vmcnt(0)
	s_cmp_gt_u32 s88, 63
	s_waitcnt vmcnt(0) lgkmcnt(0)
	s_barrier
	s_cbranch_scc1 .Lbi_8
	s_mov_b32 s99, 8
	s_branch .Lbs_entry

; #define LAS __attribute__((address_space(3)))
; DI void grid_bar(unsigned* bar, volatile LAS unsigned* st, int wid) {
;     asm volatile("s_waitcnt vmcnt(0)" ::: "memory");
;     __syncthreads();
;     if (wid == 0) {
.LBB0_1101:
	s_cmp_gt_i32 s35, 10
	s_cselect_b64 s[4:5], -1, 0
	s_and_b64 s[2:3], s[2:3], s[4:5]
	s_andn2_b64 vcc, exec, s[2:3]
	s_cbranch_vccnz .LBB0_1157
	s_load_dwordx2 s[8:9], s[0:1], 0xa8
	s_waitcnt vmcnt(0)
	s_cmp_gt_u32 s88, 63
	s_waitcnt vmcnt(0) lgkmcnt(0)
	s_barrier
	s_cbranch_scc1 .Lbi_9
	s_mov_b32 s99, 9
	s_branch .Lbs_entry

; #define LAS __attribute__((address_space(3)))
; DI void grid_bar(unsigned* bar, volatile LAS unsigned* st, int wid) {
;     asm volatile("s_waitcnt vmcnt(0)" ::: "memory");
;     __syncthreads();
;     if (wid == 0) {
.LBB0_1196:
	s_cmp_gt_i32 s35, 11
	s_cselect_b64 s[2:3], -1, 0
	s_and_b64 s[4:5], s[8:9], s[2:3]
	s_andn2_b64 vcc, exec, s[4:5]
	s_cbranch_vccnz .LBB0_1252
	s_load_dwordx2 s[8:9], s[0:1], 0xa8
	s_waitcnt vmcnt(0)
	s_cmp_gt_u32 s88, 63
	s_waitcnt vmcnt(0) lgkmcnt(0)
	s_barrier
	s_cbranch_scc1 .Lbi_10
	s_mov_b32 s99, 10
	s_branch .Lbs_entry

; #define LAS __attribute__((address_space(3)))
; DI void grid_bar(unsigned* bar, volatile LAS unsigned* st, int wid) {
;     asm volatile("s_waitcnt vmcnt(0)" ::: "memory");
;     __syncthreads();
;     if (wid == 0) {
.Lconv_skip_4:
	s_cmp_gt_i32 s35, 12
	s_cselect_b64 s[2:3], -1, 0
	s_and_b64 s[4:5], s[4:5], s[2:3]
	s_andn2_b64 vcc, exec, s[4:5]
	s_cbranch_vccnz .LBB0_1321
	s_load_dwordx2 s[8:9], s[0:1], 0xa8
	s_waitcnt vmcnt(0)
	s_cmp_gt_u32 s88, 63
	s_waitcnt vmcnt(0) lgkmcnt(0)
	s_barrier
	s_cbranch_scc1 .Lbi_11
	s_mov_b32 s99, 11
	s_branch .Lbs_entry

; #define LAS __attribute__((address_space(3)))
; DI void grid_bar(unsigned* bar, volatile LAS unsigned* st, int wid) {
;     asm volatile("s_waitcnt vmcnt(0)" ::: "memory");
;     __syncthreads();
;     if (wid == 0) {
.LBB0_1360:
	s_cmp_gt_i32 s35, 13
	s_cselect_b64 s[2:3], -1, 0
	s_and_b64 s[4:5], s[8:9], s[2:3]
	s_andn2_b64 vcc, exec, s[4:5]
	s_cbranch_vccnz .LBB0_1416
	s_load_dwordx2 s[8:9], s[0:1], 0xa8
	s_waitcnt vmcnt(0)
	s_cmp_gt_u32 s88, 63
	s_waitcnt vmcnt(0) lgkmcnt(0)
	s_barrier
	s_cbranch_scc1 .Lbi_12
	s_mov_b32 s99, 12
	s_branch .Lbs_entry
